# P7: prefetched next-unit loads waited right after the third workgroup barrier (before this unit's entry-list stores) and the counted waits in the image build removed
# speedup vs baseline: 1.0010x; 1.0010x over previous
.LBB0_874:
	s_waitcnt lgkmcnt(0)
	s_barrier
	s_waitcnt vmcnt(0)
	s_and_saveexec_b64 s[18:19], s[0:1]
	s_cbranch_execz .LBB0_854
	s_mul_i32 s46, s50, 0x600
	s_mul_hi_i32 s22, s50, 0x600
	s_add_u32 s46, s53, s46
	s_addc_u32 s47, s54, s22
	s_cmp_eq_u32 s59, 0
	s_cbranch_scc1 .LBB0_877
	v_lshl_add_u32 v5, v5, 2, 0
	ds_read_b32 v5, v5 offset:33280
	s_waitcnt lgkmcnt(0)
	v_add_u32_e32 v8, v5, v7
	v_ashrrev_i32_e32 v9, 31, v8
	v_lshl_add_u64 v[8:9], v[8:9], 1, s[46:47]
	global_store_short v[8:9], v93, off
